# mix phase stream/compute role split by blockIdx bit 3 (both roles on every XCD) plus conversion spread
# speedup vs baseline: 1.0071x; 1.0040x over previous
.LBB0_108:
	v_readlane_b32 s4, v252, 0
	v_readlane_b32 s5, v252, 1
	s_add_u32 s4, s4, 0x90
	s_addc_u32 s5, s5, 0
	v_writelane_b32 v252, s4, 8
	v_mov_b32_e32 v3, 0
	v_mov_b32_e32 v226, 1
	v_writelane_b32 v252, s5, 9
	s_lshl_b32 s4, s80, 11
	s_and_b32 s4, s4, 0x3800
	v_writelane_b32 v252, s4, 10
	s_and_b32 s4, s33, 0xffffffc0
	v_writelane_b32 v252, s4, 11
	v_mov_b32_e32 v227, 0x3727c5ac
	v_readlane_b32 s28, v252, 6
	s_lshl_b32 s4, s28, 7
	v_writelane_b32 v252, s4, 12
	s_lshl_b32 s4, s28, 13
	s_lshl_b32 s23, s28, 10
	s_lshl_b32 s29, s28, 4
	s_cmp_gt_i32 s80, -1
	v_writelane_b32 v252, s4, 13
	s_cselect_b64 s[4:5], -1, 0
	v_writelane_b32 v252, s4, 14
	v_mov_b32_e32 v228, 0x260
	v_mov_b32_e32 v236, 0x42800000
	v_writelane_b32 v252, s5, 15
	s_not_b32 s4, s80
	v_writelane_b32 v252, s4, 16
	s_add_i32 s4, s28, 0xfffffe00
	s_cmp_lt_u32 s49, 64
	v_writelane_b32 v252, s4, 17
	s_cselect_b64 s[4:5], -1, 0
	v_writelane_b32 v252, s4, 18
	v_mov_b32_e32 v237, 0xff800000
	v_not_b32_e32 v238, 63
	v_writelane_b32 v252, s5, 19
	s_add_u32 s4, s0, 0x4200
	s_addc_u32 s5, s1, 0
	v_writelane_b32 v252, s4, 20
	s_mov_b32 s36, 0xffff0000
	s_nop 0
	v_writelane_b32 v252, s5, 21
	s_add_u32 s4, s0, 0x4400
	s_addc_u32 s5, s1, 0
	v_writelane_b32 v252, s4, 22
	s_nop 1
	v_writelane_b32 v252, s5, 23
	s_add_u32 s4, s0, 0x4500
	s_addc_u32 s5, s1, 0
	v_writelane_b32 v252, s4, 24
	s_nop 1
	v_writelane_b32 v252, s5, 25
	s_add_u32 s4, s0, 0x4600
	s_addc_u32 s5, s1, 0
	v_writelane_b32 v252, s4, 26
	s_nop 1
	v_writelane_b32 v252, s5, 27
	s_add_u32 s4, s0, 0x4700
	s_addc_u32 s5, s1, 0
	v_writelane_b32 v252, s4, 28
	s_nop 1
	v_writelane_b32 v252, s5, 29
	s_add_u32 s4, s0, 0x4800
	s_addc_u32 s5, s1, 0
	v_writelane_b32 v252, s4, 30
	s_nop 1
	v_writelane_b32 v252, s5, 31
	s_add_u32 s4, s0, 0x4900
	s_addc_u32 s5, s1, 0
	v_writelane_b32 v252, s4, 32
	s_nop 1
	v_writelane_b32 v252, s5, 33
	s_add_u32 s4, s0, 0x4a00
	s_addc_u32 s5, s1, 0
	v_writelane_b32 v252, s4, 34
	s_nop 1
	v_writelane_b32 v252, s5, 35
	s_add_u32 s4, s0, 0x4b00
	s_addc_u32 s5, s1, 0
	v_writelane_b32 v252, s4, 36
	s_nop 1
	v_writelane_b32 v252, s5, 37
	s_add_u32 s4, s0, 0x4c00
	s_addc_u32 s5, s1, 0
	v_writelane_b32 v252, s4, 38
	s_nop 1
	v_writelane_b32 v252, s5, 39
	s_add_u32 s4, s0, 0x4d00
	s_addc_u32 s5, s1, 0
	v_writelane_b32 v252, s4, 40
	s_nop 1
	v_writelane_b32 v252, s5, 41
	s_add_u32 s4, s0, 0x4e00
	s_addc_u32 s5, s1, 0
	v_writelane_b32 v252, s4, 42
	s_nop 1
	v_writelane_b32 v252, s5, 43
	s_add_u32 s4, s0, 0x4f00
	s_addc_u32 s5, s1, 0
	v_writelane_b32 v252, s4, 44
	s_nop 1
	v_writelane_b32 v252, s5, 45
	s_add_u32 s4, s0, 0x5000
	s_addc_u32 s5, s1, 0
	v_writelane_b32 v252, s4, 46
	s_nop 1
	v_writelane_b32 v252, s5, 47
	s_add_u32 s4, s0, 0x5100
	s_addc_u32 s5, s1, 0
	v_writelane_b32 v252, s4, 48
	s_nop 1
	v_writelane_b32 v252, s5, 49
	s_add_u32 s4, s0, 0x5200
	s_addc_u32 s5, s1, 0
	v_writelane_b32 v252, s4, 50
	s_nop 1
	v_writelane_b32 v252, s5, 51
	s_add_u32 s4, s0, 0x5300
	s_addc_u32 s5, s1, 0
	v_writelane_b32 v252, s4, 52
	s_cmp_eq_u32 s48, 15
	s_nop 0
	v_writelane_b32 v252, s5, 53
	s_cselect_b64 s[4:5], -1, 0
	v_writelane_b32 v252, s4, 54
	s_cmp_eq_u32 s48, 14
	s_nop 0
	v_writelane_b32 v252, s5, 55
	s_cselect_b64 s[4:5], -1, 0
	v_writelane_b32 v252, s4, 56
	s_cmp_eq_u32 s48, 13
	s_nop 0
	v_writelane_b32 v252, s5, 57
	s_cselect_b64 s[4:5], -1, 0
	v_writelane_b32 v252, s4, 58
	s_cmp_eq_u32 s48, 12
	s_nop 0
	v_writelane_b32 v252, s5, 59
	s_cselect_b64 s[4:5], -1, 0
	v_writelane_b32 v252, s4, 60
	s_cmp_eq_u32 s48, 11
	s_nop 0
	v_writelane_b32 v252, s5, 61
	s_cselect_b64 s[4:5], -1, 0
	v_writelane_b32 v252, s4, 62
	s_cmp_eq_u32 s48, 10
	s_nop 0
	v_writelane_b32 v252, s5, 63
	s_cselect_b64 s[4:5], -1, 0
	v_writelane_b32 v253, s4, 0
	s_cmp_eq_u32 s48, 9
	v_readlane_b32 s22, v252, 5
	v_writelane_b32 v253, s5, 1
	s_cselect_b64 s[4:5], -1, 0
	v_writelane_b32 v253, s4, 2
	s_cmp_eq_u32 s48, 8
	s_nop 0
	v_writelane_b32 v253, s5, 3
	s_cselect_b64 s[4:5], -1, 0
	v_writelane_b32 v253, s4, 4
	s_cmp_eq_u32 s48, 7
	s_nop 0
	v_writelane_b32 v253, s5, 5
	s_cselect_b64 s[4:5], -1, 0
	v_writelane_b32 v253, s4, 6
	s_cmp_eq_u32 s48, 6
	s_nop 0
	v_writelane_b32 v253, s5, 7
	s_cselect_b64 s[4:5], -1, 0
	v_writelane_b32 v253, s4, 8
	s_cmp_eq_u32 s48, 5
	s_nop 0
	v_writelane_b32 v253, s5, 9
	s_cselect_b64 s[4:5], -1, 0
	v_writelane_b32 v253, s4, 10
	s_cmp_eq_u32 s48, 4
	s_nop 0
	v_writelane_b32 v253, s5, 11
	s_cselect_b64 s[4:5], -1, 0
	v_writelane_b32 v253, s4, 12
	s_cmp_eq_u32 s48, 3
	s_nop 0
	v_writelane_b32 v253, s5, 13
	s_cselect_b64 s[4:5], -1, 0
	v_writelane_b32 v253, s4, 14
	s_cmp_eq_u32 s48, 2
	s_nop 0
	v_writelane_b32 v253, s5, 15
	s_cselect_b64 s[4:5], -1, 0
	v_writelane_b32 v253, s4, 16
	s_cmp_eq_u32 s48, 1
	s_nop 0
	v_writelane_b32 v253, s5, 17
	s_cselect_b64 s[4:5], -1, 0
	v_writelane_b32 v253, s4, 18
	s_cmp_eq_u32 s48, 0
	s_nop 0
	v_writelane_b32 v253, s5, 19
	s_cselect_b64 s[4:5], -1, 0
	v_writelane_b32 v253, s4, 20
	s_nop 1
	v_writelane_b32 v253, s5, 21
	s_lshl_b32 s4, s48, 8
	s_add_u32 s2, s2, s4
	s_addc_u32 s3, s3, 0
	s_add_u32 s2, s2, 0x1400
	s_addc_u32 s3, s3, 0
	v_writelane_b32 v253, s2, 22
	s_nop 1
	v_writelane_b32 v253, s3, 23
	s_add_u32 s2, s0, 0x7500
	s_addc_u32 s3, s1, 0
	v_writelane_b32 v253, s2, 24
	s_add_u32 s0, s0, 0x7400
	s_addc_u32 s1, s1, 0
	v_writelane_b32 v253, s3, 25
	v_writelane_b32 v253, s0, 26
	s_nop 1
	v_writelane_b32 v253, s1, 27
	s_bfe_u32 s0, s80, 0x10003
	s_cmpk_lt_i32 s80, 0x600
	v_writelane_b32 v253, s0, 28
	s_cselect_b64 s[0:1], -1, 0
	v_writelane_b32 v253, s0, 29
	s_ashr_i32 s2, s80, 8
	s_and_b32 s4, s80, 63
	v_writelane_b32 v253, s1, 30
	s_mul_hi_i32 s0, s2, 0x55555556
	s_lshr_b32 s1, s0, 31
	s_add_i32 s0, s0, s1
	s_mul_i32 s0, s0, 3
	s_sub_i32 s3, s2, s0
	s_mul_hi_i32 s0, s80, 0x2aaaaaab
	s_lshr_b32 s1, s0, 31
	s_ashr_i32 s0, s0, 7
	s_lshl_b32 s6, s3, 1
	s_add_i32 s0, s0, s1
	s_lshl_b32 s1, -1, s6
	s_andn2_b32 s5, s4, s1
	s_ashr_i32 s1, s0, 31
	s_lshl_b64 s[0:1], s[0:1], 13
	s_or_b32 s0, s0, s5
	v_writelane_b32 v253, s0, 31
	s_add_i32 s79, s29, 16
	s_nop 0
	v_writelane_b32 v253, s1, 32
	s_lshr_b32 s1, s4, s6
	s_lshl_b32 s0, s3, 8
	s_and_b32 s3, s80, 0xc0
	s_or_b32 s0, s0, s3
	s_lshl_b32 s3, s1, 7
	v_writelane_b32 v253, s6, 33
	s_add_i32 s4, s3, 0xffffff80
	v_writelane_b32 v253, s4, 34
	s_add_i32 s3, s29, s3
	v_writelane_b32 v253, s3, 35
	s_add_i32 s3, s29, 32
	v_writelane_b32 v253, s3, 36
	s_add_i32 s3, s29, 48
	v_writelane_b32 v253, s3, 37
	s_add_i32 s3, s29, 64
	v_writelane_b32 v253, s3, 38
	s_add_i32 s3, s29, 0x50
	v_writelane_b32 v253, s3, 39
	s_add_i32 s3, s29, 0x60
	v_writelane_b32 v253, s3, 40
	s_add_i32 s3, s29, 0x70
	s_ashr_i32 s1, s0, 31
	v_writelane_b32 v253, s3, 41
	s_add_i32 s3, s29, 0x80
	s_cmpk_gt_u32 s33, 0x1ff
	v_writelane_b32 v253, s3, 42
	s_cselect_b64 s[4:5], -1, 0
	v_writelane_b32 v253, s4, 43
	s_cmpk_gt_u32 s33, 0x1bf
	s_nop 0
	v_writelane_b32 v253, s5, 44
	s_cselect_b64 s[4:5], -1, 0
	v_writelane_b32 v253, s4, 45
	s_cmpk_gt_u32 s33, 0x17f
	s_nop 0
	v_writelane_b32 v253, s5, 46
	s_cselect_b64 s[4:5], -1, 0
	v_writelane_b32 v253, s4, 47
	s_cmpk_gt_u32 s33, 0x13f
	s_nop 0
	v_writelane_b32 v253, s5, 48
	s_cselect_b64 s[4:5], -1, 0
	v_writelane_b32 v253, s4, 49
	s_cmpk_gt_u32 s33, 0xff
	s_nop 0
	v_writelane_b32 v253, s5, 50
	s_cselect_b64 s[4:5], -1, 0
	v_writelane_b32 v253, s4, 51
	s_cmpk_gt_u32 s33, 0xbf
	s_nop 0
	v_writelane_b32 v253, s5, 52
	s_cselect_b64 s[4:5], -1, 0
	v_writelane_b32 v253, s4, 53
	s_cmpk_gt_u32 s33, 0x7f
	s_nop 0
	v_writelane_b32 v253, s5, 54
	s_cselect_b64 s[4:5], -1, 0
	v_writelane_b32 v253, s4, 55
	s_cmp_gt_u32 s33, 63
	s_nop 0
	v_writelane_b32 v253, s5, 56
	s_cselect_b64 s[4:5], -1, 0
	v_writelane_b32 v253, s4, 57
	s_cmpk_lt_i32 s80, 0x200
	s_nop 0
	v_writelane_b32 v253, s5, 58
	s_cselect_b64 s[4:5], -1, 0
	v_writelane_b32 v253, s4, 59
	s_ashr_i32 s3, s2, 31
	s_lshl_b32 s30, s28, 5
	v_writelane_b32 v253, s5, 60
	s_lshl_b64 s[4:5], s[2:3], 13
	s_lshl_b32 s2, s80, 7
	v_writelane_b32 v253, s2, 61
	s_and_b32 s2, s2, 0x1f80
	s_or_b32 s4, s4, s2
	v_writelane_b32 v253, s4, 62
	s_bfe_u32 s2, s80, 0x20006
	s_nop 0
	v_writelane_b32 v253, s5, 63
	s_lshl_b32 s4, s2, 7
	s_lshl_b32 s5, s2, 8
	s_lshl_b32 s2, s80, 1
	s_cmpk_lt_i32 s2, 0x200
	v_writelane_b32 v254, s2, 0
	s_cselect_b64 s[2:3], -1, 0
	v_writelane_b32 v254, s2, 1
	s_cmpk_lt_i32 s80, 0x180
	s_nop 0
	v_writelane_b32 v254, s3, 2
	s_cselect_b64 s[2:3], -1, 0
	v_writelane_b32 v254, s2, 3
	s_cmp_lt_u32 s33, 64
	s_nop 0
	v_writelane_b32 v254, s3, 4
	s_cselect_b64 s[2:3], -1, 0
	v_writelane_b32 v254, s2, 5
	s_or_b32 s8, s29, 3
	s_or_b32 s9, s29, 4
	v_writelane_b32 v254, s3, 6
	s_sub_i32 s3, 0x7f, s29
	v_writelane_b32 v254, s3, 7
	s_sub_i32 s3, 0x7e, s29
	v_writelane_b32 v254, s3, 8
	s_or_b32 s3, s29, 2
	s_sub_i32 s6, 0x7f, s3
	v_writelane_b32 v254, s6, 9
	s_sub_i32 s6, 0x7f, s8
	v_writelane_b32 v254, s6, 10
	s_sub_i32 s6, 0x7f, s9
	s_or_b32 s10, s29, 5
	v_writelane_b32 v254, s6, 11
	s_sub_i32 s6, 0x7f, s10
	s_or_b32 s11, s29, 6
	v_writelane_b32 v254, s6, 12
	s_sub_i32 s6, 0x7f, s11
	s_or_b32 s12, s29, 7
	v_writelane_b32 v254, s6, 13
	s_sub_i32 s6, 0x7f, s12
	s_or_b32 s13, s29, 8
	v_writelane_b32 v254, s6, 14
	s_sub_i32 s6, 0x7f, s13
	s_or_b32 s14, s29, 9
	v_writelane_b32 v254, s6, 15
	s_sub_i32 s6, 0x7f, s14
	s_or_b32 s15, s29, 10
	v_writelane_b32 v254, s6, 16
	s_sub_i32 s6, 0x7f, s15
	s_or_b32 s16, s29, 11
	v_writelane_b32 v254, s6, 17
	s_sub_i32 s6, 0x7f, s16
	s_or_b32 s17, s29, 12
	v_writelane_b32 v254, s6, 18
	s_sub_i32 s6, 0x7f, s17
	s_or_b32 s18, s29, 13
	v_writelane_b32 v254, s6, 19
	s_sub_i32 s6, 0x7f, s18
	s_or_b32 s19, s29, 14
	v_writelane_b32 v254, s6, 20
	s_sub_i32 s6, 0x7f, s19
	s_or_b32 s20, s29, 15
	v_writelane_b32 v254, s6, 21
	s_sub_i32 s6, 0x7f, s20
	s_or_b32 s2, s29, 1
	v_writelane_b32 v254, s6, 22
	s_lshl_b32 s6, s80, 9
	s_cmpk_lt_i32 s80, 0x100
	v_writelane_b32 v254, s6, 23
	s_cselect_b64 s[6:7], -1, 0
	s_lshl_b32 s21, s22, 5
	v_writelane_b32 v254, s6, 24
	s_cmp_lt_i32 s80, 0
	v_cvt_f32_u32_e32 v210, s2
	v_writelane_b32 v254, s7, 25
	s_cselect_b64 s[6:7], -1, 0
	v_writelane_b32 v254, s6, 26
	v_cvt_f32_u32_e32 v212, s8
	v_cvt_f32_u32_e32 v211, s3
	v_writelane_b32 v254, s7, 27
	s_lshl_b32 s6, s28, 11
	s_cmpk_lt_u32 s33, 0x80
	v_writelane_b32 v254, s6, 28
	s_cselect_b64 s[6:7], -1, 0
	v_writelane_b32 v254, s6, 29
	s_cmpk_lt_u32 s33, 0x100
	v_cvt_f32_u32_e32 v213, s9
	v_writelane_b32 v254, s7, 30
	s_cselect_b64 s[6:7], -1, 0
	v_writelane_b32 v254, s6, 31
	v_cvt_f32_u32_e32 v214, s10
	v_cvt_f32_u32_e32 v215, s11
	v_writelane_b32 v254, s7, 32
	s_and_b64 s[6:7], s[6:7], exec
	s_cselect_b32 s6, 0, 0x80
	v_writelane_b32 v254, s6, 33
	s_lshl_b32 s6, s28, 8
	s_and_b32 s6, s6, 0x300
	v_writelane_b32 v254, s6, 34
	s_lshl_b32 s6, s28, 12
	v_writelane_b32 v254, s6, 35
	v_writelane_b32 v254, s23, 36
	s_add_i32 s6, s23, 0
	v_writelane_b32 v254, s6, 37
	s_cmp_lt_i32 s22, 0
	s_mul_i32 s6, s22, 33
	s_cselect_b32 s6, s6, s21
	v_readlane_b32 s7, v252, 4
	s_add_i32 s6, s6, s7
	s_ashr_i32 s7, s6, 31
	s_lshr_b32 s7, s7, 28
	s_add_i32 s7, s6, s7
	s_and_b32 s21, s7, -16
	s_ashr_i32 s7, s7, 4
	s_lshl_b32 s7, s7, 2
	s_sub_i32 s6, s6, s21
	s_sub_i32 s21, 64, s7
	s_min_i32 s21, s21, 4
	s_abs_i32 s22, s21
	v_cvt_f32_u32_e32 v0, s22
	s_sub_i32 s23, 0, s22
	v_cvt_f32_u32_e32 v216, s12
	v_cvt_f32_u32_e32 v217, s13
	v_rcp_iflag_f32_e32 v0, v0
	v_cvt_f32_u32_e32 v218, s14
	v_cvt_f32_u32_e32 v219, s15
	v_cvt_f32_u32_e32 v220, s16
	v_mul_f32_e32 v0, 0x4f7ffffe, v0
	v_cvt_u32_f32_e32 v0, v0
	v_cvt_f32_u32_e32 v221, s17
	v_cvt_f32_u32_e32 v222, s18
	v_cvt_f32_u32_e32 v223, s19
	v_readfirstlane_b32 s24, v0
	s_mul_i32 s23, s23, s24
	s_mul_hi_u32 s23, s24, s23
	s_add_i32 s24, s24, s23
	s_abs_i32 s23, s6
	s_mul_hi_u32 s24, s23, s24
	s_mul_i32 s25, s24, s22
	s_sub_i32 s23, s23, s25
	s_xor_b32 s25, s6, s21
	s_ashr_i32 s25, s25, 31
	s_add_i32 s26, s24, 1
	s_sub_i32 s27, s23, s22
	s_cmp_ge_u32 s23, s22
	s_cselect_b32 s24, s26, s24
	s_cselect_b32 s23, s27, s23
	s_add_i32 s26, s24, 1
	s_cmp_ge_u32 s23, s22
	s_cselect_b32 s2, s26, s24
	s_xor_b32 s2, s2, s25
	s_sub_i32 s8, s2, s25
	s_mul_i32 s2, s8, s21
	s_sub_i32 s2, s6, s2
	s_add_i32 s6, s7, s2
	s_lshl_b32 s2, s80, 2
	s_or_b32 s2, s2, 1
	v_writelane_b32 v254, s2, 38
	v_writelane_b32 v254, s30, 39
	s_or_b32 s2, s30, 16
	s_ashr_i32 s7, s6, 31
	v_writelane_b32 v254, s2, 40
	s_lshl_b32 s2, s80, 8
	v_writelane_b32 v254, s2, 41
	s_lshl_b64 s[2:3], s[6:7], 17
	s_ashr_i32 s9, s8, 31
	v_writelane_b32 v254, s2, 42
	v_cvt_f32_u32_e32 v224, s20
	s_movk_i32 s33, 0x7fff
	v_writelane_b32 v254, s3, 43
	s_lshl_b64 s[2:3], s[8:9], 17
	v_writelane_b32 v254, s2, 44
	v_mbcnt_lo_u32_b32 v0, -1, 0
	v_mbcnt_hi_u32_b32 v229, -1, v0
	v_writelane_b32 v254, s3, 45
	s_mov_b32 s2, s6
	v_writelane_b32 v254, s2, 46
	s_mov_b32 s15, 0
	s_nop 0
	v_writelane_b32 v254, s3, 47
	s_lshl_b64 s[2:3], s[6:7], 19
	v_writelane_b32 v254, s2, 48
	s_nop 1
	v_writelane_b32 v254, s3, 49
	s_mov_b32 s2, s8
	v_writelane_b32 v254, s2, 50
	s_nop 1
	v_writelane_b32 v254, s3, 51
	s_lshl_b64 s[2:3], s[8:9], 19
	v_writelane_b32 v254, s2, 52
	s_nop 1
	v_writelane_b32 v254, s3, 53
	s_lshl_b64 s[2:3], s[80:81], 17
	v_writelane_b32 v254, s2, 54
	s_nop 1
	v_writelane_b32 v254, s3, 55
	s_lshl_b64 s[2:3], s[80:81], 16
	s_add_u32 s2, s2, 0x19400000
	v_writelane_b32 v254, s2, 56
	s_addc_u32 s2, s3, 0
	v_writelane_b32 v254, s2, 57
	s_lshl_b64 s[0:1], s[0:1], 1
	v_writelane_b32 v254, s0, 58
	s_mov_b32 s3, 0
	s_mul_i32 s2, s28, 0x160
	v_writelane_b32 v254, s1, 59
	s_lshl_b32 s0, s4, 1
	v_writelane_b32 v254, s0, 60
	s_lshl_b32 s0, s5, 1
	v_writelane_b32 v254, s0, 61
	v_writelane_b32 v254, s29, 62
	s_add_i32 s0, s29, 0x4000
	v_writelane_b32 v254, s0, 63
	s_add_i32 s0, 0, 0x20160
	v_writelane_b32 v255, s0, 0
	s_add_i32 s0, 0, 0x20164
	v_writelane_b32 v255, s0, 1
	s_mov_b64 s[0:1], -1
	v_writelane_b32 v255, s0, 2
	s_nop 1
	v_writelane_b32 v255, s1, 3
	s_lshl_b64 s[0:1], s[2:3], 1
	v_writelane_b32 v255, s0, 4
	s_nop 1
	v_writelane_b32 v255, s1, 5
	v_writelane_b32 v255, s80, 6
	s_nop 1
	v_writelane_b32 v255, s81, 7
	v_writelane_b32 v255, s79, 8
	s_branch .LBB0_113
